# FFN1-down and out-proj K-loops: A-fragment reads from one persistent base VGPR with immediate offsets (4 VALU per iteration removed)
# speedup vs baseline: 1.0000x; 1.0000x over previous
.LBB0_729:
	s_add_u32 s15, s18, 0x100
	s_addc_u32 s62, s19, 0
	v_lshl_add_u64 v[148:149], s[10:11], 0, v[140:141]
	v_lshl_add_u64 v[150:151], s[10:11], 0, v[142:143]
	s_mov_b32 s63, -2
	s_mov_b64 s[18:19], 0
	v_add_u32_e32 v232, 0x10000, v153
.LBB0_730:
	ds_read_b128 v[156:159], v232
	ds_read_b128 v[160:163], v232 offset:1024
	ds_read_b128 v[164:167], v232 offset:2048
	ds_read_b128 v[168:171], v232 offset:3072
	s_add_u32 s20, s10, s18
	ds_read_b128 v[172:175], v232 offset:16384
	ds_read_b128 v[176:179], v232 offset:17408
	ds_read_b128 v[180:183], v232 offset:18432
	ds_read_b128 v[184:187], v232 offset:19456
	s_addc_u32 s21, s11, s19
	s_add_u32 s20, s20, 0x100
	s_addc_u32 s21, s21, 0
	s_add_u32 s64, s15, s18
	s_addc_u32 s65, s62, s19
	s_cmpk_eq_i32 s18, 0x1500
	s_cselect_b32 s29, s17, s21
	s_cselect_b32 s28, s16, s20
	s_cselect_b32 s21, s1, s65
	s_cselect_b32 s20, s0, s64
	v_lshl_add_u64 v[220:221], v[148:149], 0, s[18:19]
	s_add_i32 m0, s51, 0xc000
	ds_read_b128 v[188:191], v154
	ds_read_b128 v[192:195], v154 offset:1024
	ds_read_b128 v[196:199], v154 offset:2048
	ds_read_b128 v[200:203], v154 offset:3072
	ds_read_b128 v[204:207], v154 offset:4096
	ds_read_b128 v[208:211], v154 offset:5120
	ds_read_b128 v[212:215], v154 offset:6144
	ds_read_b128 v[216:219], v154 offset:7168
	global_load_lds_dwordx4 v[220:221], off
	v_lshl_add_u64 v[220:221], v[150:151], 0, s[18:19]
	s_add_i32 m0, s51, 0xe000
	s_nop 0
	global_load_lds_dwordx4 v[220:221], off
	s_waitcnt vmcnt(8)
	s_waitcnt lgkmcnt(0)
	s_barrier
	v_mfma_f32_16x16x32_bf16 v[126:129], v[156:159], v[188:191], v[126:129]
	v_mfma_f32_16x16x32_bf16 v[122:125], v[164:167], v[188:191], v[122:125]
	v_mfma_f32_16x16x32_bf16 v[110:113], v[156:159], v[196:199], v[110:113]
	v_mfma_f32_16x16x32_bf16 v[106:109], v[164:167], v[196:199], v[106:109]
	v_mfma_f32_16x16x32_bf16 v[94:97], v[156:159], v[204:207], v[94:97]
	v_mfma_f32_16x16x32_bf16 v[90:93], v[164:167], v[204:207], v[90:93]
	v_mfma_f32_16x16x32_bf16 v[78:81], v[156:159], v[212:215], v[78:81]
	v_mfma_f32_16x16x32_bf16 v[74:77], v[164:167], v[212:215], v[74:77]
	v_mfma_f32_16x16x32_bf16 v[126:129], v[160:163], v[192:195], v[126:129]
	v_mfma_f32_16x16x32_bf16 v[122:125], v[168:171], v[192:195], v[122:125]
	v_mfma_f32_16x16x32_bf16 v[110:113], v[160:163], v[200:203], v[110:113]
	v_mfma_f32_16x16x32_bf16 v[106:109], v[168:171], v[200:203], v[106:109]
	v_mfma_f32_16x16x32_bf16 v[94:97], v[160:163], v[208:211], v[94:97]
	v_mfma_f32_16x16x32_bf16 v[90:93], v[168:171], v[208:211], v[90:93]
	v_mfma_f32_16x16x32_bf16 v[78:81], v[160:163], v[216:219], v[78:81]
	v_mfma_f32_16x16x32_bf16 v[74:77], v[168:171], v[216:219], v[74:77]
	v_mfma_f32_16x16x32_bf16 v[118:121], v[172:175], v[188:191], v[118:121]
	v_mfma_f32_16x16x32_bf16 v[114:117], v[180:183], v[188:191], v[114:117]
	v_mfma_f32_16x16x32_bf16 v[102:105], v[172:175], v[196:199], v[102:105]
	v_mfma_f32_16x16x32_bf16 v[98:101], v[180:183], v[196:199], v[98:101]
	v_mfma_f32_16x16x32_bf16 v[86:89], v[172:175], v[204:207], v[86:89]
	v_mfma_f32_16x16x32_bf16 v[82:85], v[180:183], v[204:207], v[82:85]
	v_mfma_f32_16x16x32_bf16 v[70:73], v[172:175], v[212:215], v[70:73]
	v_mfma_f32_16x16x32_bf16 v[66:69], v[180:183], v[212:215], v[66:69]
	v_mfma_f32_16x16x32_bf16 v[118:121], v[176:179], v[192:195], v[118:121]
	v_mfma_f32_16x16x32_bf16 v[114:117], v[184:187], v[192:195], v[114:117]
	v_mfma_f32_16x16x32_bf16 v[102:105], v[176:179], v[200:203], v[102:105]
	v_mfma_f32_16x16x32_bf16 v[98:101], v[184:187], v[200:203], v[98:101]
	v_mfma_f32_16x16x32_bf16 v[86:89], v[176:179], v[208:211], v[86:89]
	v_mfma_f32_16x16x32_bf16 v[82:85], v[184:187], v[208:211], v[82:85]
	v_mfma_f32_16x16x32_bf16 v[70:73], v[176:179], v[216:219], v[70:73]
	v_mfma_f32_16x16x32_bf16 v[66:69], v[184:187], v[216:219], v[66:69]
	s_barrier
	s_add_i32 s64, s58, s35
	s_mov_b32 m0, s64
	ds_read_b128 v[188:191], v154 offset:16384
	ds_read_b128 v[192:195], v154 offset:17408
	ds_read_b128 v[196:199], v154 offset:18432
	ds_read_b128 v[200:203], v154 offset:19456
	ds_read_b128 v[204:207], v154 offset:20480
	ds_read_b128 v[208:211], v154 offset:21504
	ds_read_b128 v[212:215], v154 offset:22528
	ds_read_b128 v[216:219], v154 offset:23552
	global_load_lds_dwordx4 v132, s[20:21]
	s_add_i32 m0, s64, 0x2000
	s_add_u32 s64, s20, 0xb0000
	s_addc_u32 s65, s21, 0
	s_add_i32 s66, s59, s35
	global_load_lds_dwordx4 v136, s[20:21]
	s_mov_b32 m0, s66
	s_nop 0
	global_load_lds_dwordx4 v132, s[64:65]
	s_add_i32 m0, s66, 0x2000
	s_nop 0
	global_load_lds_dwordx4 v136, s[64:65]
	s_mov_b32 m0, s51
	s_nop 0
	global_load_lds_dwordx4 v130, s[28:29]
	s_mov_b32 m0, s52
	s_nop 0
	global_load_lds_dwordx4 v134, s[28:29]
	s_waitcnt vmcnt(8)
	s_waitcnt lgkmcnt(0)
	s_barrier
	v_mfma_f32_16x16x32_bf16 v[62:65], v[156:159], v[188:191], v[62:65]
	v_mfma_f32_16x16x32_bf16 v[58:61], v[164:167], v[188:191], v[58:61]
	v_mfma_f32_16x16x32_bf16 v[46:49], v[156:159], v[196:199], v[46:49]
	v_mfma_f32_16x16x32_bf16 v[42:45], v[164:167], v[196:199], v[42:45]
	v_mfma_f32_16x16x32_bf16 v[30:33], v[156:159], v[204:207], v[30:33]
	v_mfma_f32_16x16x32_bf16 v[26:29], v[164:167], v[204:207], v[26:29]
	v_mfma_f32_16x16x32_bf16 v[14:17], v[156:159], v[212:215], v[14:17]
	v_mfma_f32_16x16x32_bf16 v[10:13], v[164:167], v[212:215], v[10:13]
	v_mfma_f32_16x16x32_bf16 v[62:65], v[160:163], v[192:195], v[62:65]
	v_mfma_f32_16x16x32_bf16 v[58:61], v[168:171], v[192:195], v[58:61]
	v_mfma_f32_16x16x32_bf16 v[46:49], v[160:163], v[200:203], v[46:49]
	v_mfma_f32_16x16x32_bf16 v[42:45], v[168:171], v[200:203], v[42:45]
	v_mfma_f32_16x16x32_bf16 v[30:33], v[160:163], v[208:211], v[30:33]
	v_mfma_f32_16x16x32_bf16 v[26:29], v[168:171], v[208:211], v[26:29]
	v_mfma_f32_16x16x32_bf16 v[14:17], v[160:163], v[216:219], v[14:17]
	v_mfma_f32_16x16x32_bf16 v[10:13], v[168:171], v[216:219], v[10:13]
	v_mfma_f32_16x16x32_bf16 v[54:57], v[172:175], v[188:191], v[54:57]
	v_mfma_f32_16x16x32_bf16 v[50:53], v[180:183], v[188:191], v[50:53]
	v_mfma_f32_16x16x32_bf16 v[38:41], v[172:175], v[196:199], v[38:41]
	v_mfma_f32_16x16x32_bf16 v[34:37], v[180:183], v[196:199], v[34:37]
	v_mfma_f32_16x16x32_bf16 v[22:25], v[172:175], v[204:207], v[22:25]
	v_mfma_f32_16x16x32_bf16 v[18:21], v[180:183], v[204:207], v[18:21]
	v_mfma_f32_16x16x32_bf16 v[6:9], v[172:175], v[212:215], v[6:9]
	v_mfma_f32_16x16x32_bf16 v[2:5], v[180:183], v[212:215], v[2:5]
	v_mfma_f32_16x16x32_bf16 v[54:57], v[176:179], v[192:195], v[54:57]
	v_mfma_f32_16x16x32_bf16 v[50:53], v[184:187], v[192:195], v[50:53]
	v_mfma_f32_16x16x32_bf16 v[38:41], v[176:179], v[200:203], v[38:41]
	v_mfma_f32_16x16x32_bf16 v[34:37], v[184:187], v[200:203], v[34:37]
	v_mfma_f32_16x16x32_bf16 v[22:25], v[176:179], v[208:211], v[22:25]
	v_mfma_f32_16x16x32_bf16 v[18:21], v[184:187], v[208:211], v[18:21]
	v_mfma_f32_16x16x32_bf16 v[6:9], v[176:179], v[216:219], v[6:9]
	v_mfma_f32_16x16x32_bf16 v[2:5], v[184:187], v[216:219], v[2:5]
	s_barrier
	s_add_i32 s64, 0, 0x18000
	s_add_i32 s65, 0, 0x1c000
	ds_read_b128 v[156:159], v232 offset:32768
	ds_read_b128 v[160:163], v232 offset:33792
	ds_read_b128 v[164:167], v232 offset:34816
	ds_read_b128 v[168:171], v232 offset:35840
	ds_read_b128 v[172:175], v232 offset:49152
	ds_read_b128 v[176:179], v232 offset:50176
	ds_read_b128 v[180:183], v232 offset:51200
	ds_read_b128 v[184:187], v232 offset:52224
	s_add_u32 s98, s28, 0xb0000
	s_addc_u32 s99, s29, 0
	s_mov_b32 m0, s53
	ds_read_b128 v[188:191], v154 offset:32768
	ds_read_b128 v[192:195], v154 offset:33792
	ds_read_b128 v[196:199], v154 offset:34816
	ds_read_b128 v[200:203], v154 offset:35840
	ds_read_b128 v[204:207], v154 offset:36864
	ds_read_b128 v[208:211], v154 offset:37888
	ds_read_b128 v[212:215], v154 offset:38912
	ds_read_b128 v[216:219], v154 offset:39936
	global_load_lds_dwordx4 v130, s[98:99]
	s_mov_b32 m0, s54
	s_nop 0
	global_load_lds_dwordx4 v134, s[98:99]
	s_waitcnt vmcnt(8)
	s_waitcnt lgkmcnt(0)
	s_barrier
	v_mfma_f32_16x16x32_bf16 v[126:129], v[156:159], v[188:191], v[126:129]
	v_mfma_f32_16x16x32_bf16 v[122:125], v[164:167], v[188:191], v[122:125]
	v_mfma_f32_16x16x32_bf16 v[110:113], v[156:159], v[196:199], v[110:113]
	v_mfma_f32_16x16x32_bf16 v[106:109], v[164:167], v[196:199], v[106:109]
	v_mfma_f32_16x16x32_bf16 v[94:97], v[156:159], v[204:207], v[94:97]
	v_mfma_f32_16x16x32_bf16 v[90:93], v[164:167], v[204:207], v[90:93]
	v_mfma_f32_16x16x32_bf16 v[78:81], v[156:159], v[212:215], v[78:81]
	v_mfma_f32_16x16x32_bf16 v[74:77], v[164:167], v[212:215], v[74:77]
	v_mfma_f32_16x16x32_bf16 v[126:129], v[160:163], v[192:195], v[126:129]
	v_mfma_f32_16x16x32_bf16 v[122:125], v[168:171], v[192:195], v[122:125]
	v_mfma_f32_16x16x32_bf16 v[110:113], v[160:163], v[200:203], v[110:113]
	v_mfma_f32_16x16x32_bf16 v[106:109], v[168:171], v[200:203], v[106:109]
	v_mfma_f32_16x16x32_bf16 v[94:97], v[160:163], v[208:211], v[94:97]
	v_mfma_f32_16x16x32_bf16 v[90:93], v[168:171], v[208:211], v[90:93]
	v_mfma_f32_16x16x32_bf16 v[78:81], v[160:163], v[216:219], v[78:81]
	v_mfma_f32_16x16x32_bf16 v[74:77], v[168:171], v[216:219], v[74:77]
	v_mfma_f32_16x16x32_bf16 v[118:121], v[172:175], v[188:191], v[118:121]
	v_mfma_f32_16x16x32_bf16 v[114:117], v[180:183], v[188:191], v[114:117]
	v_mfma_f32_16x16x32_bf16 v[102:105], v[172:175], v[196:199], v[102:105]
	v_mfma_f32_16x16x32_bf16 v[98:101], v[180:183], v[196:199], v[98:101]
	v_mfma_f32_16x16x32_bf16 v[86:89], v[172:175], v[204:207], v[86:89]
	v_mfma_f32_16x16x32_bf16 v[82:85], v[180:183], v[204:207], v[82:85]
	v_mfma_f32_16x16x32_bf16 v[70:73], v[172:175], v[212:215], v[70:73]
	v_mfma_f32_16x16x32_bf16 v[66:69], v[180:183], v[212:215], v[66:69]
	v_mfma_f32_16x16x32_bf16 v[118:121], v[176:179], v[192:195], v[118:121]
	v_mfma_f32_16x16x32_bf16 v[114:117], v[184:187], v[192:195], v[114:117]
	v_mfma_f32_16x16x32_bf16 v[102:105], v[176:179], v[200:203], v[102:105]
	v_mfma_f32_16x16x32_bf16 v[98:101], v[184:187], v[200:203], v[98:101]
	v_mfma_f32_16x16x32_bf16 v[86:89], v[176:179], v[208:211], v[86:89]
	v_mfma_f32_16x16x32_bf16 v[82:85], v[184:187], v[208:211], v[82:85]
	v_mfma_f32_16x16x32_bf16 v[70:73], v[176:179], v[216:219], v[70:73]
	v_mfma_f32_16x16x32_bf16 v[66:69], v[184:187], v[216:219], v[66:69]
	s_barrier
	s_add_i32 s98, s64, s35
	s_add_i32 m0, s98, 0xffffff80
	ds_read_b128 v[188:191], v154 offset:49152
	ds_read_b128 v[192:195], v154 offset:50176
	ds_read_b128 v[196:199], v154 offset:51200
	ds_read_b128 v[200:203], v154 offset:52224
	ds_read_b128 v[204:207], v154 offset:53248
	ds_read_b128 v[208:211], v154 offset:54272
	ds_read_b128 v[212:215], v154 offset:55296
	ds_read_b128 v[216:219], v154 offset:56320
	global_load_lds_dwordx4 v132, s[20:21] offset:128
	s_add_i32 m0, s98, 0x1f80
	s_add_i32 s98, s65, s35
	global_load_lds_dwordx4 v136, s[20:21] offset:128
	s_add_u32 s20, s20, 0xb0080
	s_addc_u32 s21, s21, 0
	s_mov_b32 m0, s98
	s_nop 0
	global_load_lds_dwordx4 v132, s[20:21]
	s_add_i32 m0, s98, 0x2000
	s_nop 0
	global_load_lds_dwordx4 v136, s[20:21]
	s_add_i32 m0, s56, 0xffffff80
	s_nop 0
	global_load_lds_dwordx4 v130, s[28:29] offset:128
	s_add_i32 m0, s57, 0xffffff80
	s_nop 0
	global_load_lds_dwordx4 v134, s[28:29] offset:128
	s_waitcnt vmcnt(8)
	s_waitcnt lgkmcnt(0)
	s_barrier
	v_mfma_f32_16x16x32_bf16 v[62:65], v[156:159], v[188:191], v[62:65]
	v_mfma_f32_16x16x32_bf16 v[58:61], v[164:167], v[188:191], v[58:61]
	v_mfma_f32_16x16x32_bf16 v[46:49], v[156:159], v[196:199], v[46:49]
	v_mfma_f32_16x16x32_bf16 v[42:45], v[164:167], v[196:199], v[42:45]
	v_mfma_f32_16x16x32_bf16 v[30:33], v[156:159], v[204:207], v[30:33]
	v_mfma_f32_16x16x32_bf16 v[26:29], v[164:167], v[204:207], v[26:29]
	v_mfma_f32_16x16x32_bf16 v[14:17], v[156:159], v[212:215], v[14:17]
	v_mfma_f32_16x16x32_bf16 v[10:13], v[164:167], v[212:215], v[10:13]
	v_mfma_f32_16x16x32_bf16 v[62:65], v[160:163], v[192:195], v[62:65]
	v_mfma_f32_16x16x32_bf16 v[58:61], v[168:171], v[192:195], v[58:61]
	v_mfma_f32_16x16x32_bf16 v[46:49], v[160:163], v[200:203], v[46:49]
	v_mfma_f32_16x16x32_bf16 v[42:45], v[168:171], v[200:203], v[42:45]
	v_mfma_f32_16x16x32_bf16 v[30:33], v[160:163], v[208:211], v[30:33]
	v_mfma_f32_16x16x32_bf16 v[26:29], v[168:171], v[208:211], v[26:29]
	v_mfma_f32_16x16x32_bf16 v[14:17], v[160:163], v[216:219], v[14:17]
	v_mfma_f32_16x16x32_bf16 v[10:13], v[168:171], v[216:219], v[10:13]
	v_mfma_f32_16x16x32_bf16 v[54:57], v[172:175], v[188:191], v[54:57]
	v_mfma_f32_16x16x32_bf16 v[50:53], v[180:183], v[188:191], v[50:53]
	v_mfma_f32_16x16x32_bf16 v[38:41], v[172:175], v[196:199], v[38:41]
	v_mfma_f32_16x16x32_bf16 v[34:37], v[180:183], v[196:199], v[34:37]
	v_mfma_f32_16x16x32_bf16 v[22:25], v[172:175], v[204:207], v[22:25]
	v_mfma_f32_16x16x32_bf16 v[18:21], v[180:183], v[204:207], v[18:21]
	v_mfma_f32_16x16x32_bf16 v[6:9], v[172:175], v[212:215], v[6:9]
	v_mfma_f32_16x16x32_bf16 v[2:5], v[180:183], v[212:215], v[2:5]
	v_mfma_f32_16x16x32_bf16 v[54:57], v[176:179], v[192:195], v[54:57]
	v_mfma_f32_16x16x32_bf16 v[50:53], v[184:187], v[192:195], v[50:53]
	v_mfma_f32_16x16x32_bf16 v[38:41], v[176:179], v[200:203], v[38:41]
	v_mfma_f32_16x16x32_bf16 v[34:37], v[184:187], v[200:203], v[34:37]
	v_mfma_f32_16x16x32_bf16 v[22:25], v[176:179], v[208:211], v[22:25]
	v_mfma_f32_16x16x32_bf16 v[18:21], v[184:187], v[208:211], v[18:21]
	v_mfma_f32_16x16x32_bf16 v[6:9], v[176:179], v[216:219], v[6:9]
	v_mfma_f32_16x16x32_bf16 v[2:5], v[184:187], v[216:219], v[2:5]
	s_barrier
	s_add_i32 s63, s63, 2
	s_add_u32 s18, s18, 0x100
	s_addc_u32 s19, s19, 0
	s_cmp_gt_u32 s63, 41
	s_cbranch_scc0 .LBB0_730
	s_add_u32 s18, s15, 0xffffff00
	s_addc_u32 s19, s62, -1
	s_and_b64 vcc, exec, s[4:5]
	s_cbranch_vccnz .LBB0_733
	v_mov_b32_e32 v2, 0
	v_mov_b32_e32 v3, 0
	v_mov_b64_e32 v[4:5], v[2:3]
	v_mov_b64_e32 v[6:7], v[2:3]
	v_mov_b64_e32 v[8:9], v[2:3]
	v_mov_b64_e32 v[10:11], v[2:3]
	v_mov_b64_e32 v[12:13], v[2:3]
	v_mov_b64_e32 v[14:15], v[2:3]
	v_mov_b64_e32 v[16:17], v[2:3]
	v_mov_b64_e32 v[18:19], v[2:3]
	v_mov_b64_e32 v[20:21], v[2:3]
	v_mov_b64_e32 v[22:23], v[2:3]
	v_mov_b64_e32 v[24:25], v[2:3]
	v_mov_b64_e32 v[26:27], v[2:3]
	v_mov_b64_e32 v[28:29], v[2:3]
	v_mov_b64_e32 v[30:31], v[2:3]
	v_mov_b64_e32 v[32:33], v[2:3]
	v_mov_b64_e32 v[34:35], v[2:3]
	v_mov_b64_e32 v[36:37], v[2:3]
	v_mov_b64_e32 v[38:39], v[2:3]
	v_mov_b64_e32 v[40:41], v[2:3]
	v_mov_b64_e32 v[42:43], v[2:3]
	v_mov_b64_e32 v[44:45], v[2:3]
	v_mov_b64_e32 v[46:47], v[2:3]
	v_mov_b64_e32 v[48:49], v[2:3]
	v_mov_b64_e32 v[50:51], v[2:3]
	v_mov_b64_e32 v[52:53], v[2:3]
	v_mov_b64_e32 v[54:55], v[2:3]
	v_mov_b64_e32 v[56:57], v[2:3]
	v_mov_b64_e32 v[58:59], v[2:3]
	v_mov_b64_e32 v[60:61], v[2:3]
	v_mov_b64_e32 v[62:63], v[2:3]
	v_mov_b64_e32 v[64:65], v[2:3]
	v_mov_b64_e32 v[66:67], v[2:3]
	v_mov_b64_e32 v[68:69], v[2:3]
	v_mov_b64_e32 v[70:71], v[2:3]
	v_mov_b64_e32 v[72:73], v[2:3]
	v_mov_b64_e32 v[74:75], v[2:3]
	v_mov_b64_e32 v[76:77], v[2:3]
	v_mov_b64_e32 v[78:79], v[2:3]
	v_mov_b64_e32 v[80:81], v[2:3]
	v_mov_b64_e32 v[82:83], v[2:3]
	v_mov_b64_e32 v[84:85], v[2:3]
	v_mov_b64_e32 v[86:87], v[2:3]
	v_mov_b64_e32 v[88:89], v[2:3]
	v_mov_b64_e32 v[90:91], v[2:3]
	v_mov_b64_e32 v[92:93], v[2:3]
	v_mov_b64_e32 v[94:95], v[2:3]
	v_mov_b64_e32 v[96:97], v[2:3]
	v_mov_b64_e32 v[98:99], v[2:3]
	v_mov_b64_e32 v[100:101], v[2:3]
	v_mov_b64_e32 v[102:103], v[2:3]
	v_mov_b64_e32 v[104:105], v[2:3]
	v_mov_b64_e32 v[106:107], v[2:3]
	v_mov_b64_e32 v[108:109], v[2:3]
	v_mov_b64_e32 v[110:111], v[2:3]
	v_mov_b64_e32 v[112:113], v[2:3]
	v_mov_b64_e32 v[114:115], v[2:3]
	v_mov_b64_e32 v[116:117], v[2:3]
	v_mov_b64_e32 v[118:119], v[2:3]
	v_mov_b64_e32 v[120:121], v[2:3]
	v_mov_b64_e32 v[122:123], v[2:3]
	v_mov_b64_e32 v[124:125], v[2:3]
	v_mov_b64_e32 v[126:127], v[2:3]
	v_mov_b64_e32 v[128:129], v[2:3]
	s_mov_b32 s8, s60
	s_mov_b32 s50, s61
	s_mov_b64 s[10:11], s[16:17]
	s_mov_b32 s55, s14
	s_branch .LBB0_734

.LBB0_1785:
	s_add_u32 s21, s28, 0x100
	s_addc_u32 s50, s29, 0
	s_ashr_i32 s17, s16, 31
	s_lshl_b64 s[18:19], s[16:17], 19
	s_add_u32 s36, s35, s18
	s_addc_u32 s37, s40, s19
	s_and_b64 s[18:19], s[4:5], exec
	s_cselect_b32 s17, s37, s11
	s_cselect_b32 s51, s36, s10
	s_ashr_i32 s15, s14, 31
	s_lshl_b64 s[18:19], s[14:15], 19
	s_add_u32 s18, s33, s18
	s_addc_u32 s19, s34, s19
	s_and_b64 s[30:31], s[4:5], exec
	s_cselect_b32 s15, s19, s29
	s_cselect_b32 s52, s18, s28
	v_lshl_add_u64 v[148:149], s[10:11], 0, v[140:141]
	v_lshl_add_u64 v[150:151], s[10:11], 0, v[142:143]
	s_mov_b32 s53, -2
	s_mov_b64 s[38:39], 0
	v_add_u32_e32 v232, 0x10000, v153
.LBB0_1786:
	ds_read_b128 v[156:159], v232
	ds_read_b128 v[160:163], v232 offset:1024
	ds_read_b128 v[164:167], v232 offset:2048
	ds_read_b128 v[168:171], v232 offset:3072
	s_add_u32 s28, s10, s38
	ds_read_b128 v[172:175], v232 offset:16384
	ds_read_b128 v[176:179], v232 offset:17408
	ds_read_b128 v[180:183], v232 offset:18432
	ds_read_b128 v[184:187], v232 offset:19456
	s_addc_u32 s29, s11, s39
	s_add_u32 s28, s28, 0x100
	s_addc_u32 s29, s29, 0
	s_add_u32 s54, s21, s38
	s_addc_u32 s55, s50, s39
	s_cmpk_eq_i32 s38, 0x700
	s_cselect_b32 s31, s17, s29
	s_cselect_b32 s30, s51, s28
	s_cselect_b32 s29, s15, s55
	s_cselect_b32 s28, s52, s54
	v_lshl_add_u64 v[220:221], v[148:149], 0, s[38:39]
	s_add_i32 m0, s1, 0xc000
	ds_read_b128 v[188:191], v154
	ds_read_b128 v[192:195], v154 offset:1024
	ds_read_b128 v[196:199], v154 offset:2048
	ds_read_b128 v[200:203], v154 offset:3072
	ds_read_b128 v[204:207], v154 offset:4096
	ds_read_b128 v[208:211], v154 offset:5120
	ds_read_b128 v[212:215], v154 offset:6144
	ds_read_b128 v[216:219], v154 offset:7168
	global_load_lds_dwordx4 v[220:221], off
	v_lshl_add_u64 v[220:221], v[150:151], 0, s[38:39]
	s_add_i32 m0, s1, 0xe000
	s_nop 0
	global_load_lds_dwordx4 v[220:221], off
	s_waitcnt vmcnt(8)
	s_waitcnt lgkmcnt(0)
	s_barrier
	v_mfma_f32_16x16x32_bf16 v[126:129], v[156:159], v[188:191], v[126:129]
	v_mfma_f32_16x16x32_bf16 v[122:125], v[164:167], v[188:191], v[122:125]
	v_mfma_f32_16x16x32_bf16 v[110:113], v[156:159], v[196:199], v[110:113]
	v_mfma_f32_16x16x32_bf16 v[106:109], v[164:167], v[196:199], v[106:109]
	v_mfma_f32_16x16x32_bf16 v[94:97], v[156:159], v[204:207], v[94:97]
	v_mfma_f32_16x16x32_bf16 v[90:93], v[164:167], v[204:207], v[90:93]
	v_mfma_f32_16x16x32_bf16 v[78:81], v[156:159], v[212:215], v[78:81]
	v_mfma_f32_16x16x32_bf16 v[74:77], v[164:167], v[212:215], v[74:77]
	v_mfma_f32_16x16x32_bf16 v[126:129], v[160:163], v[192:195], v[126:129]
	v_mfma_f32_16x16x32_bf16 v[122:125], v[168:171], v[192:195], v[122:125]
	v_mfma_f32_16x16x32_bf16 v[110:113], v[160:163], v[200:203], v[110:113]
	v_mfma_f32_16x16x32_bf16 v[106:109], v[168:171], v[200:203], v[106:109]
	v_mfma_f32_16x16x32_bf16 v[94:97], v[160:163], v[208:211], v[94:97]
	v_mfma_f32_16x16x32_bf16 v[90:93], v[168:171], v[208:211], v[90:93]
	v_mfma_f32_16x16x32_bf16 v[78:81], v[160:163], v[216:219], v[78:81]
	v_mfma_f32_16x16x32_bf16 v[74:77], v[168:171], v[216:219], v[74:77]
	v_mfma_f32_16x16x32_bf16 v[118:121], v[172:175], v[188:191], v[118:121]
	v_mfma_f32_16x16x32_bf16 v[114:117], v[180:183], v[188:191], v[114:117]
	v_mfma_f32_16x16x32_bf16 v[102:105], v[172:175], v[196:199], v[102:105]
	v_mfma_f32_16x16x32_bf16 v[98:101], v[180:183], v[196:199], v[98:101]
	v_mfma_f32_16x16x32_bf16 v[86:89], v[172:175], v[204:207], v[86:89]
	v_mfma_f32_16x16x32_bf16 v[82:85], v[180:183], v[204:207], v[82:85]
	v_mfma_f32_16x16x32_bf16 v[70:73], v[172:175], v[212:215], v[70:73]
	v_mfma_f32_16x16x32_bf16 v[66:69], v[180:183], v[212:215], v[66:69]
	v_mfma_f32_16x16x32_bf16 v[118:121], v[176:179], v[192:195], v[118:121]
	v_mfma_f32_16x16x32_bf16 v[114:117], v[184:187], v[192:195], v[114:117]
	v_mfma_f32_16x16x32_bf16 v[102:105], v[176:179], v[200:203], v[102:105]
	v_mfma_f32_16x16x32_bf16 v[98:101], v[184:187], v[200:203], v[98:101]
	v_mfma_f32_16x16x32_bf16 v[86:89], v[176:179], v[208:211], v[86:89]
	v_mfma_f32_16x16x32_bf16 v[82:85], v[184:187], v[208:211], v[82:85]
	v_mfma_f32_16x16x32_bf16 v[70:73], v[176:179], v[216:219], v[70:73]
	v_mfma_f32_16x16x32_bf16 v[66:69], v[184:187], v[216:219], v[66:69]
	s_barrier
	s_add_i32 s54, s48, s41
	s_mov_b32 m0, s54
	ds_read_b128 v[188:191], v154 offset:16384
	ds_read_b128 v[192:195], v154 offset:17408
	ds_read_b128 v[196:199], v154 offset:18432
	ds_read_b128 v[200:203], v154 offset:19456
	ds_read_b128 v[204:207], v154 offset:20480
	ds_read_b128 v[208:211], v154 offset:21504
	ds_read_b128 v[212:215], v154 offset:22528
	ds_read_b128 v[216:219], v154 offset:23552
	global_load_lds_dwordx4 v132, s[28:29]
	s_add_i32 m0, s54, 0x2000
	s_add_u32 s54, s28, 0x40000
	s_addc_u32 s55, s29, 0
	s_add_i32 s56, s49, s41
	global_load_lds_dwordx4 v136, s[28:29]
	s_mov_b32 m0, s56
	s_nop 0
	global_load_lds_dwordx4 v132, s[54:55]
	s_add_i32 m0, s56, 0x2000
	s_nop 0
	global_load_lds_dwordx4 v136, s[54:55]
	s_mov_b32 m0, s1
	s_nop 0
	global_load_lds_dwordx4 v130, s[30:31]
	s_mov_b32 m0, s42
	s_nop 0
	global_load_lds_dwordx4 v134, s[30:31]
	s_waitcnt vmcnt(8)
	s_waitcnt lgkmcnt(0)
	s_barrier
	v_mfma_f32_16x16x32_bf16 v[62:65], v[156:159], v[188:191], v[62:65]
	v_mfma_f32_16x16x32_bf16 v[58:61], v[164:167], v[188:191], v[58:61]
	v_mfma_f32_16x16x32_bf16 v[46:49], v[156:159], v[196:199], v[46:49]
	v_mfma_f32_16x16x32_bf16 v[42:45], v[164:167], v[196:199], v[42:45]
	v_mfma_f32_16x16x32_bf16 v[30:33], v[156:159], v[204:207], v[30:33]
	v_mfma_f32_16x16x32_bf16 v[26:29], v[164:167], v[204:207], v[26:29]
	v_mfma_f32_16x16x32_bf16 v[14:17], v[156:159], v[212:215], v[14:17]
	v_mfma_f32_16x16x32_bf16 v[10:13], v[164:167], v[212:215], v[10:13]
	v_mfma_f32_16x16x32_bf16 v[62:65], v[160:163], v[192:195], v[62:65]
	v_mfma_f32_16x16x32_bf16 v[58:61], v[168:171], v[192:195], v[58:61]
	v_mfma_f32_16x16x32_bf16 v[46:49], v[160:163], v[200:203], v[46:49]
	v_mfma_f32_16x16x32_bf16 v[42:45], v[168:171], v[200:203], v[42:45]
	v_mfma_f32_16x16x32_bf16 v[30:33], v[160:163], v[208:211], v[30:33]
	v_mfma_f32_16x16x32_bf16 v[26:29], v[168:171], v[208:211], v[26:29]
	v_mfma_f32_16x16x32_bf16 v[14:17], v[160:163], v[216:219], v[14:17]
	v_mfma_f32_16x16x32_bf16 v[10:13], v[168:171], v[216:219], v[10:13]
	v_mfma_f32_16x16x32_bf16 v[54:57], v[172:175], v[188:191], v[54:57]
	v_mfma_f32_16x16x32_bf16 v[50:53], v[180:183], v[188:191], v[50:53]
	v_mfma_f32_16x16x32_bf16 v[38:41], v[172:175], v[196:199], v[38:41]
	v_mfma_f32_16x16x32_bf16 v[34:37], v[180:183], v[196:199], v[34:37]
	v_mfma_f32_16x16x32_bf16 v[22:25], v[172:175], v[204:207], v[22:25]
	v_mfma_f32_16x16x32_bf16 v[18:21], v[180:183], v[204:207], v[18:21]
	v_mfma_f32_16x16x32_bf16 v[6:9], v[172:175], v[212:215], v[6:9]
	v_mfma_f32_16x16x32_bf16 v[2:5], v[180:183], v[212:215], v[2:5]
	v_mfma_f32_16x16x32_bf16 v[54:57], v[176:179], v[192:195], v[54:57]
	v_mfma_f32_16x16x32_bf16 v[50:53], v[184:187], v[192:195], v[50:53]
	v_mfma_f32_16x16x32_bf16 v[38:41], v[176:179], v[200:203], v[38:41]
	v_mfma_f32_16x16x32_bf16 v[34:37], v[184:187], v[200:203], v[34:37]
	v_mfma_f32_16x16x32_bf16 v[22:25], v[176:179], v[208:211], v[22:25]
	v_mfma_f32_16x16x32_bf16 v[18:21], v[184:187], v[208:211], v[18:21]
	v_mfma_f32_16x16x32_bf16 v[6:9], v[176:179], v[216:219], v[6:9]
	v_mfma_f32_16x16x32_bf16 v[2:5], v[184:187], v[216:219], v[2:5]
	s_barrier
	s_add_i32 s54, 0, 0x18000
	s_add_i32 s55, 0, 0x1c000
	ds_read_b128 v[156:159], v232 offset:32768
	ds_read_b128 v[160:163], v232 offset:33792
	ds_read_b128 v[164:167], v232 offset:34816
	ds_read_b128 v[168:171], v232 offset:35840
	ds_read_b128 v[172:175], v232 offset:49152
	ds_read_b128 v[176:179], v232 offset:50176
	ds_read_b128 v[180:183], v232 offset:51200
	ds_read_b128 v[184:187], v232 offset:52224
	s_add_u32 s98, s30, 0x40000
	s_addc_u32 s99, s31, 0
	s_mov_b32 m0, s43
	ds_read_b128 v[188:191], v154 offset:32768
	ds_read_b128 v[192:195], v154 offset:33792
	ds_read_b128 v[196:199], v154 offset:34816
	ds_read_b128 v[200:203], v154 offset:35840
	ds_read_b128 v[204:207], v154 offset:36864
	ds_read_b128 v[208:211], v154 offset:37888
	ds_read_b128 v[212:215], v154 offset:38912
	ds_read_b128 v[216:219], v154 offset:39936
	global_load_lds_dwordx4 v130, s[98:99]
	s_mov_b32 m0, s44
	s_nop 0
	global_load_lds_dwordx4 v134, s[98:99]
	s_waitcnt vmcnt(8)
	s_waitcnt lgkmcnt(0)
	s_barrier
	v_mfma_f32_16x16x32_bf16 v[126:129], v[156:159], v[188:191], v[126:129]
	v_mfma_f32_16x16x32_bf16 v[122:125], v[164:167], v[188:191], v[122:125]
	v_mfma_f32_16x16x32_bf16 v[110:113], v[156:159], v[196:199], v[110:113]
	v_mfma_f32_16x16x32_bf16 v[106:109], v[164:167], v[196:199], v[106:109]
	v_mfma_f32_16x16x32_bf16 v[94:97], v[156:159], v[204:207], v[94:97]
	v_mfma_f32_16x16x32_bf16 v[90:93], v[164:167], v[204:207], v[90:93]
	v_mfma_f32_16x16x32_bf16 v[78:81], v[156:159], v[212:215], v[78:81]
	v_mfma_f32_16x16x32_bf16 v[74:77], v[164:167], v[212:215], v[74:77]
	v_mfma_f32_16x16x32_bf16 v[126:129], v[160:163], v[192:195], v[126:129]
	v_mfma_f32_16x16x32_bf16 v[122:125], v[168:171], v[192:195], v[122:125]
	v_mfma_f32_16x16x32_bf16 v[110:113], v[160:163], v[200:203], v[110:113]
	v_mfma_f32_16x16x32_bf16 v[106:109], v[168:171], v[200:203], v[106:109]
	v_mfma_f32_16x16x32_bf16 v[94:97], v[160:163], v[208:211], v[94:97]
	v_mfma_f32_16x16x32_bf16 v[90:93], v[168:171], v[208:211], v[90:93]
	v_mfma_f32_16x16x32_bf16 v[78:81], v[160:163], v[216:219], v[78:81]
	v_mfma_f32_16x16x32_bf16 v[74:77], v[168:171], v[216:219], v[74:77]
	v_mfma_f32_16x16x32_bf16 v[118:121], v[172:175], v[188:191], v[118:121]
	v_mfma_f32_16x16x32_bf16 v[114:117], v[180:183], v[188:191], v[114:117]
	v_mfma_f32_16x16x32_bf16 v[102:105], v[172:175], v[196:199], v[102:105]
	v_mfma_f32_16x16x32_bf16 v[98:101], v[180:183], v[196:199], v[98:101]
	v_mfma_f32_16x16x32_bf16 v[86:89], v[172:175], v[204:207], v[86:89]
	v_mfma_f32_16x16x32_bf16 v[82:85], v[180:183], v[204:207], v[82:85]
	v_mfma_f32_16x16x32_bf16 v[70:73], v[172:175], v[212:215], v[70:73]
	v_mfma_f32_16x16x32_bf16 v[66:69], v[180:183], v[212:215], v[66:69]
	v_mfma_f32_16x16x32_bf16 v[118:121], v[176:179], v[192:195], v[118:121]
	v_mfma_f32_16x16x32_bf16 v[114:117], v[184:187], v[192:195], v[114:117]
	v_mfma_f32_16x16x32_bf16 v[102:105], v[176:179], v[200:203], v[102:105]
	v_mfma_f32_16x16x32_bf16 v[98:101], v[184:187], v[200:203], v[98:101]
	v_mfma_f32_16x16x32_bf16 v[86:89], v[176:179], v[208:211], v[86:89]
	v_mfma_f32_16x16x32_bf16 v[82:85], v[184:187], v[208:211], v[82:85]
	v_mfma_f32_16x16x32_bf16 v[70:73], v[176:179], v[216:219], v[70:73]
	v_mfma_f32_16x16x32_bf16 v[66:69], v[184:187], v[216:219], v[66:69]
	s_barrier
	s_add_i32 s98, s54, s41
	s_add_i32 m0, s98, 0xffffff80
	ds_read_b128 v[188:191], v154 offset:49152
	ds_read_b128 v[192:195], v154 offset:50176
	ds_read_b128 v[196:199], v154 offset:51200
	ds_read_b128 v[200:203], v154 offset:52224
	ds_read_b128 v[204:207], v154 offset:53248
	ds_read_b128 v[208:211], v154 offset:54272
	ds_read_b128 v[212:215], v154 offset:55296
	ds_read_b128 v[216:219], v154 offset:56320
	global_load_lds_dwordx4 v132, s[28:29] offset:128
	s_add_i32 m0, s98, 0x1f80
	s_add_i32 s98, s55, s41
	global_load_lds_dwordx4 v136, s[28:29] offset:128
	s_add_u32 s28, s28, 0x40080
	s_addc_u32 s29, s29, 0
	s_mov_b32 m0, s98
	s_nop 0
	global_load_lds_dwordx4 v132, s[28:29]
	s_add_i32 m0, s98, 0x2000
	s_nop 0
	global_load_lds_dwordx4 v136, s[28:29]
	s_add_i32 m0, s46, 0xffffff80
	s_nop 0
	global_load_lds_dwordx4 v130, s[30:31] offset:128
	s_add_i32 m0, s47, 0xffffff80
	s_nop 0
	global_load_lds_dwordx4 v134, s[30:31] offset:128
	s_waitcnt vmcnt(8)
	s_waitcnt lgkmcnt(0)
	s_barrier
	v_mfma_f32_16x16x32_bf16 v[62:65], v[156:159], v[188:191], v[62:65]
	v_mfma_f32_16x16x32_bf16 v[58:61], v[164:167], v[188:191], v[58:61]
	v_mfma_f32_16x16x32_bf16 v[46:49], v[156:159], v[196:199], v[46:49]
	v_mfma_f32_16x16x32_bf16 v[42:45], v[164:167], v[196:199], v[42:45]
	v_mfma_f32_16x16x32_bf16 v[30:33], v[156:159], v[204:207], v[30:33]
	v_mfma_f32_16x16x32_bf16 v[26:29], v[164:167], v[204:207], v[26:29]
	v_mfma_f32_16x16x32_bf16 v[14:17], v[156:159], v[212:215], v[14:17]
	v_mfma_f32_16x16x32_bf16 v[10:13], v[164:167], v[212:215], v[10:13]
	v_mfma_f32_16x16x32_bf16 v[62:65], v[160:163], v[192:195], v[62:65]
	v_mfma_f32_16x16x32_bf16 v[58:61], v[168:171], v[192:195], v[58:61]
	v_mfma_f32_16x16x32_bf16 v[46:49], v[160:163], v[200:203], v[46:49]
	v_mfma_f32_16x16x32_bf16 v[42:45], v[168:171], v[200:203], v[42:45]
	v_mfma_f32_16x16x32_bf16 v[30:33], v[160:163], v[208:211], v[30:33]
	v_mfma_f32_16x16x32_bf16 v[26:29], v[168:171], v[208:211], v[26:29]
	v_mfma_f32_16x16x32_bf16 v[14:17], v[160:163], v[216:219], v[14:17]
	v_mfma_f32_16x16x32_bf16 v[10:13], v[168:171], v[216:219], v[10:13]
	v_mfma_f32_16x16x32_bf16 v[54:57], v[172:175], v[188:191], v[54:57]
	v_mfma_f32_16x16x32_bf16 v[50:53], v[180:183], v[188:191], v[50:53]
	v_mfma_f32_16x16x32_bf16 v[38:41], v[172:175], v[196:199], v[38:41]
	v_mfma_f32_16x16x32_bf16 v[34:37], v[180:183], v[196:199], v[34:37]
	v_mfma_f32_16x16x32_bf16 v[22:25], v[172:175], v[204:207], v[22:25]
	v_mfma_f32_16x16x32_bf16 v[18:21], v[180:183], v[204:207], v[18:21]
	v_mfma_f32_16x16x32_bf16 v[6:9], v[172:175], v[212:215], v[6:9]
	v_mfma_f32_16x16x32_bf16 v[2:5], v[180:183], v[212:215], v[2:5]
	v_mfma_f32_16x16x32_bf16 v[54:57], v[176:179], v[192:195], v[54:57]
	v_mfma_f32_16x16x32_bf16 v[50:53], v[184:187], v[192:195], v[50:53]
	v_mfma_f32_16x16x32_bf16 v[38:41], v[176:179], v[200:203], v[38:41]
	v_mfma_f32_16x16x32_bf16 v[34:37], v[184:187], v[200:203], v[34:37]
	v_mfma_f32_16x16x32_bf16 v[22:25], v[176:179], v[208:211], v[22:25]
	v_mfma_f32_16x16x32_bf16 v[18:21], v[184:187], v[208:211], v[18:21]
	v_mfma_f32_16x16x32_bf16 v[6:9], v[176:179], v[216:219], v[6:9]
	v_mfma_f32_16x16x32_bf16 v[2:5], v[184:187], v[216:219], v[2:5]
	s_barrier
	s_add_i32 s53, s53, 2
	s_add_u32 s38, s38, 0x100
	s_addc_u32 s39, s39, 0
	s_cmp_gt_u32 s53, 13
	s_cbranch_scc0 .LBB0_1786
	s_add_u32 s28, s21, 0xffffff00
	s_addc_u32 s29, s50, -1
	s_andn2_b64 vcc, exec, s[4:5]
	s_cbranch_vccnz .LBB0_1789
	v_mov_b32_e32 v2, 0
	v_mov_b32_e32 v3, 0
	v_mov_b64_e32 v[4:5], v[2:3]
	v_mov_b64_e32 v[6:7], v[2:3]
	v_mov_b64_e32 v[8:9], v[2:3]
	v_mov_b64_e32 v[10:11], v[2:3]
	v_mov_b64_e32 v[12:13], v[2:3]
	v_mov_b64_e32 v[14:15], v[2:3]
	v_mov_b64_e32 v[16:17], v[2:3]
	v_mov_b64_e32 v[18:19], v[2:3]
	v_mov_b64_e32 v[20:21], v[2:3]
	v_mov_b64_e32 v[22:23], v[2:3]
	v_mov_b64_e32 v[24:25], v[2:3]
	v_mov_b64_e32 v[26:27], v[2:3]
	v_mov_b64_e32 v[28:29], v[2:3]
	v_mov_b64_e32 v[30:31], v[2:3]
	v_mov_b64_e32 v[32:33], v[2:3]
	v_mov_b64_e32 v[34:35], v[2:3]
	v_mov_b64_e32 v[36:37], v[2:3]
	v_mov_b64_e32 v[38:39], v[2:3]
	v_mov_b64_e32 v[40:41], v[2:3]
	v_mov_b64_e32 v[42:43], v[2:3]
	v_mov_b64_e32 v[44:45], v[2:3]
	v_mov_b64_e32 v[46:47], v[2:3]
	v_mov_b64_e32 v[48:49], v[2:3]
	v_mov_b64_e32 v[50:51], v[2:3]
	v_mov_b64_e32 v[52:53], v[2:3]
	v_mov_b64_e32 v[54:55], v[2:3]
	v_mov_b64_e32 v[56:57], v[2:3]
	v_mov_b64_e32 v[58:59], v[2:3]
	v_mov_b64_e32 v[60:61], v[2:3]
	v_mov_b64_e32 v[62:63], v[2:3]
	v_mov_b64_e32 v[64:65], v[2:3]
	v_mov_b64_e32 v[66:67], v[2:3]
	v_mov_b64_e32 v[68:69], v[2:3]
	v_mov_b64_e32 v[70:71], v[2:3]
	v_mov_b64_e32 v[72:73], v[2:3]
	v_mov_b64_e32 v[74:75], v[2:3]
	v_mov_b64_e32 v[76:77], v[2:3]
	v_mov_b64_e32 v[78:79], v[2:3]
	v_mov_b64_e32 v[80:81], v[2:3]
	v_mov_b64_e32 v[82:83], v[2:3]
	v_mov_b64_e32 v[84:85], v[2:3]
	v_mov_b64_e32 v[86:87], v[2:3]
	v_mov_b64_e32 v[88:89], v[2:3]
	v_mov_b64_e32 v[90:91], v[2:3]
	v_mov_b64_e32 v[92:93], v[2:3]
	v_mov_b64_e32 v[94:95], v[2:3]
	v_mov_b64_e32 v[96:97], v[2:3]
	v_mov_b64_e32 v[98:99], v[2:3]
	v_mov_b64_e32 v[100:101], v[2:3]
	v_mov_b64_e32 v[102:103], v[2:3]
	v_mov_b64_e32 v[104:105], v[2:3]
	v_mov_b64_e32 v[106:107], v[2:3]
	v_mov_b64_e32 v[108:109], v[2:3]
	v_mov_b64_e32 v[110:111], v[2:3]
	v_mov_b64_e32 v[112:113], v[2:3]
	v_mov_b64_e32 v[114:115], v[2:3]
	v_mov_b64_e32 v[116:117], v[2:3]
	v_mov_b64_e32 v[118:119], v[2:3]
	v_mov_b64_e32 v[120:121], v[2:3]
	v_mov_b64_e32 v[122:123], v[2:3]
	v_mov_b64_e32 v[124:125], v[2:3]
	v_mov_b64_e32 v[126:127], v[2:3]
	v_mov_b64_e32 v[128:129], v[2:3]
	s_mov_b32 s6, s14
	s_mov_b32 s0, s16
	s_mov_b64 s[10:11], s[36:37]
	s_mov_b32 s45, s20
	s_andn2_b64 vcc, exec, s[2:3]
	s_cbranch_vccnz .LBB0_1790
	s_branch .LBB0_1791
